# P7: U tile stores marked nt (streamed 256MiB write no longer evicts re-read XB/W_up) on top of pipelined P5 merge epilogue
# speedup vs baseline: 1.0042x; 1.0032x over previous
.LBB0_956:
	v_and_b32_e32 v131, 64, v209
	v_xor_b32_e32 v130, 16, v209
	v_add_u32_e32 v131, 64, v131
	v_cmp_lt_i32_e32 vcc, v130, v131
	v_lshl_add_u32 v170, s37, 8, v172
	v_ashrrev_i32_e32 v171, 31, v170
	v_cndmask_b32_e32 v130, v209, v130, vcc
	v_lshlrev_b32_e32 v192, 2, v130
	v_xor_b32_e32 v130, 32, v209
	v_cmp_lt_i32_e32 vcc, v130, v131
	v_or_b32_e32 v166, 16, v170
	v_ashrrev_i32_e32 v167, 31, v166
	v_cndmask_b32_e32 v130, v209, v130, vcc
	v_lshlrev_b32_e32 v191, 2, v130
	v_lshlrev_b64 v[130:131], 6, v[170:171]
	v_lshl_add_u64 v[130:131], v[148:149], 0, v[130:131]
	global_load_dwordx4 v[130:133], v[130:131], off
	v_lshlrev_b64 v[134:135], 6, v[166:167]
	v_lshl_add_u64 v[134:135], v[148:149], 0, v[134:135]
	global_load_dwordx4 v[134:137], v[134:135], off
	v_or_b32_e32 v162, 32, v170
	v_ashrrev_i32_e32 v163, 31, v162
	v_lshlrev_b64 v[138:139], 6, v[162:163]
	v_lshl_add_u64 v[138:139], v[148:149], 0, v[138:139]
	global_load_dwordx4 v[138:141], v[138:139], off
	v_or_b32_e32 v158, 48, v170
	v_ashrrev_i32_e32 v159, 31, v158
	v_lshlrev_b64 v[156:157], 6, v[158:159]
	v_lshl_add_u64 v[156:157], v[148:149], 0, v[156:157]
	global_load_dwordx4 v[180:183], v[156:157], off
	v_add_u32_e32 v168, 0x80, v170
	v_ashrrev_i32_e32 v169, 31, v168
	v_add_u32_e32 v164, 0x90, v170
	v_ashrrev_i32_e32 v165, 31, v164
	v_add_u32_e32 v160, 0xa0, v170
	v_ashrrev_i32_e32 v161, 31, v160
	v_add_u32_e32 v156, 0xb0, v170
	v_ashrrev_i32_e32 v157, 31, v156
	s_lshl_b32 s2, s26, 8
	s_ashr_i32 s3, s2, 31
	s_lshl_b64 s[16:17], s[2:3], 1
	v_readlane_b32 s2, v254, 18
	s_lshl_b32 s26, s2, 1
	s_mov_b64 s[2:3], -1
	s_andn2_b64 vcc, exec, s[4:5]
	s_waitcnt vmcnt(0)
	v_mul_f32_e32 v131, v175, v131
	v_fmac_f32_e32 v131, v174, v130
	v_mul_f32_e32 v130, v185, v133
	v_fmac_f32_e32 v130, v184, v132
	v_add_f32_e32 v130, v131, v130
	ds_bpermute_b32 v131, v192, v130
	s_waitcnt lgkmcnt(0)
	v_add_f32_e32 v130, v130, v131
	ds_bpermute_b32 v131, v191, v130
	s_waitcnt lgkmcnt(0)
	v_add_f32_e32 v130, v130, v131
	v_fmamk_f32 v130, v130, 0x3a800000, v207
	v_rsq_f32_e32 v190, v130
	v_mul_f32_e32 v130, v175, v135
	v_mul_f32_e32 v131, v185, v137
	v_fmac_f32_e32 v130, v174, v134
	v_fmac_f32_e32 v131, v184, v136
	v_add_f32_e32 v130, v130, v131
	ds_bpermute_b32 v131, v192, v130
	v_mul_f32_e32 v122, v122, v190
	v_mul_f32_e32 v123, v123, v190
	v_mul_f32_e32 v126, v126, v190
	v_mul_f32_e32 v127, v127, v190
	s_waitcnt lgkmcnt(0)
	v_add_f32_e32 v130, v130, v131
	ds_bpermute_b32 v131, v191, v130
	v_max_f32_e32 v122, 0, v122
	v_max_f32_e32 v123, 0, v123
	v_max_f32_e32 v126, 0, v126
	v_max_f32_e32 v127, 0, v127
	s_waitcnt lgkmcnt(0)
	v_add_f32_e32 v130, v130, v131
	v_fmamk_f32 v130, v130, 0x3a800000, v207
	v_rsq_f32_e32 v189, v130
	v_mul_f32_e32 v130, v175, v139
	v_mul_f32_e32 v131, v185, v141
	v_fmac_f32_e32 v130, v174, v138
	v_fmac_f32_e32 v131, v184, v140
	v_add_f32_e32 v130, v130, v131
	ds_bpermute_b32 v131, v192, v130
	v_pk_mul_f32 v[126:127], v[126:127], v[126:127]
	v_mul_f32_e32 v128, v128, v190
	v_mul_f32_e32 v129, v129, v190
	v_max_f32_e32 v128, 0, v128
	s_waitcnt lgkmcnt(0)
	v_add_f32_e32 v130, v130, v131
	ds_bpermute_b32 v131, v191, v130
	v_max_f32_e32 v129, 0, v129
	v_pk_mul_f32 v[128:129], v[128:129], v[128:129]
	v_mul_f32_e32 v110, v110, v190
	v_mul_f32_e32 v111, v111, v190
	s_waitcnt lgkmcnt(0)
	v_add_f32_e32 v130, v130, v131
	v_fmamk_f32 v130, v130, 0x3a800000, v207
	v_rsq_f32_e32 v188, v130
	v_mul_f32_e32 v130, v175, v181
	v_mul_f32_e32 v131, v185, v183
	v_fmac_f32_e32 v130, v174, v180
	v_fmac_f32_e32 v131, v184, v182
	v_add_f32_e32 v130, v130, v131
	ds_bpermute_b32 v131, v192, v130
	v_max_f32_e32 v110, 0, v110
	v_max_f32_e32 v111, 0, v111
	v_mul_f32_e32 v118, v118, v190
	v_mul_f32_e32 v119, v119, v190
	s_waitcnt lgkmcnt(0)
	v_add_f32_e32 v130, v130, v131
	ds_bpermute_b32 v131, v191, v130
	v_mul_f32_e32 v120, v120, v190
	v_mul_f32_e32 v121, v121, v190
	v_max_f32_e32 v118, 0, v118
	v_max_f32_e32 v119, 0, v119
	s_waitcnt lgkmcnt(0)
	v_add_f32_e32 v130, v130, v131
	v_fmamk_f32 v130, v130, 0x3a800000, v207
	v_rsq_f32_e32 v187, v130
	v_lshlrev_b64 v[130:131], 6, v[168:169]
	v_lshl_add_u64 v[130:131], v[148:149], 0, v[130:131]
	global_load_dwordx4 v[180:183], v[130:131], off
	v_lshlrev_b64 v[130:131], 6, v[164:165]
	v_lshl_add_u64 v[130:131], v[148:149], 0, v[130:131]
	global_load_dwordx4 v[138:141], v[130:131], off
	v_lshlrev_b64 v[130:131], 6, v[160:161]
	v_lshl_add_u64 v[130:131], v[148:149], 0, v[130:131]
	global_load_dwordx4 v[134:137], v[130:131], off
	v_lshlrev_b64 v[130:131], 6, v[156:157]
	v_lshl_add_u64 v[130:131], v[148:149], 0, v[130:131]
	global_load_dwordx4 v[130:133], v[130:131], off
	v_max_f32_e32 v120, 0, v120
	v_max_f32_e32 v121, 0, v121
	v_pk_mul_f32 v[118:119], v[118:119], v[118:119]
	v_pk_mul_f32 v[120:121], v[120:121], v[120:121]
	v_mul_f32_e32 v106, v106, v189
	v_mul_f32_e32 v107, v107, v189
	v_max_f32_e32 v106, 0, v106
	v_max_f32_e32 v107, 0, v107
	v_mul_f32_e32 v94, v94, v189
	v_mul_f32_e32 v95, v95, v189
	v_max_f32_e32 v94, 0, v94
	v_max_f32_e32 v95, 0, v95
	v_mul_f32_e32 v102, v102, v189
	v_mul_f32_e32 v103, v103, v189
	v_mul_f32_e32 v104, v104, v189
	v_mul_f32_e32 v105, v105, v189
	v_max_f32_e32 v102, 0, v102
	v_max_f32_e32 v103, 0, v103
	v_max_f32_e32 v104, 0, v104
	v_max_f32_e32 v105, 0, v105
	v_pk_mul_f32 v[102:103], v[102:103], v[102:103]
	v_pk_mul_f32 v[104:105], v[104:105], v[104:105]
	v_mul_f32_e32 v90, v90, v188
	v_mul_f32_e32 v91, v91, v188
	v_max_f32_e32 v90, 0, v90
	v_max_f32_e32 v91, 0, v91
	v_mul_f32_e32 v78, v78, v188
	v_mul_f32_e32 v79, v79, v188
	v_max_f32_e32 v78, 0, v78
	v_max_f32_e32 v79, 0, v79
	v_mul_f32_e32 v86, v86, v188
	v_mul_f32_e32 v87, v87, v188
	v_mul_f32_e32 v88, v88, v188
	v_mul_f32_e32 v89, v89, v188
	v_max_f32_e32 v86, 0, v86
	v_max_f32_e32 v87, 0, v87
	v_max_f32_e32 v88, 0, v88
	v_max_f32_e32 v89, 0, v89
	v_pk_mul_f32 v[86:87], v[86:87], v[86:87]
	v_pk_mul_f32 v[88:89], v[88:89], v[88:89]
	v_mul_f32_e32 v74, v74, v187
	v_mul_f32_e32 v75, v75, v187
	v_max_f32_e32 v74, 0, v74
	v_max_f32_e32 v75, 0, v75
	v_mul_f32_e32 v66, v66, v187
	v_mul_f32_e32 v67, v67, v187
	v_max_f32_e32 v66, 0, v66
	v_max_f32_e32 v67, 0, v67
	v_mul_f32_e32 v70, v70, v187
	v_mul_f32_e32 v71, v71, v187
	v_mul_f32_e32 v72, v72, v187
	v_mul_f32_e32 v73, v73, v187
	v_max_f32_e32 v70, 0, v70
	v_max_f32_e32 v71, 0, v71
	v_max_f32_e32 v72, 0, v72
	v_max_f32_e32 v73, 0, v73
	v_pk_mul_f32 v[70:71], v[70:71], v[70:71]
	v_pk_mul_f32 v[72:73], v[72:73], v[72:73]
	s_waitcnt vmcnt(3)
	v_mul_f32_e32 v181, v175, v181
	v_fmac_f32_e32 v181, v174, v180
	v_mul_f32_e32 v180, v185, v183
	s_waitcnt vmcnt(2)
	v_mul_f32_e32 v139, v175, v139
	v_fmac_f32_e32 v139, v174, v138
	v_mul_f32_e32 v138, v185, v141
	s_waitcnt vmcnt(1)
	v_mul_f32_e32 v135, v175, v135
	v_fmac_f32_e32 v135, v174, v134
	v_mul_f32_e32 v134, v185, v137
	s_waitcnt vmcnt(0)
	v_mul_f32_e32 v131, v175, v131
	v_fmac_f32_e32 v134, v184, v136
	v_fmac_f32_e32 v131, v174, v130
	v_mul_f32_e32 v130, v185, v133
	v_pk_mul_f32 v[136:137], v[122:123], v[122:123]
	v_mul_f32_e32 v122, v124, v190
	v_mul_f32_e32 v123, v125, v190
	v_fmac_f32_e32 v130, v184, v132
	v_lshlrev_b64 v[132:133], 13, v[170:171]
	v_max_f32_e32 v122, 0, v122
	v_max_f32_e32 v123, 0, v123
	v_fmac_f32_e32 v138, v184, v140
	v_pk_mul_f32 v[140:141], v[122:123], v[122:123]
	v_cvt_pk_bf16_f32 v122, v126, v127
	v_lshl_add_u64 v[126:127], s[0:1], 0, v[132:133]
	v_lshl_add_u64 v[126:127], v[126:127], 0, s[16:17]
	v_lshl_add_u64 v[126:127], v[126:127], 0, s[26:27]
	v_cvt_pk_bf16_f32 v123, v128, v129
	v_cvt_pk_bf16_f32 v124, v136, v137
	v_cvt_pk_bf16_f32 v125, v140, v141
	v_lshl_add_u64 v[126:127], v[126:127], 0, v[154:155]
	global_store_dwordx4 v[126:127], v[122:125], off nt
	v_fmac_f32_e32 v180, v184, v182
	v_add_f32_e32 v180, v181, v180
	v_pk_mul_f32 v[122:123], v[110:111], v[110:111]
	v_mul_f32_e32 v110, v112, v190
	v_mul_f32_e32 v111, v113, v190
	v_max_f32_e32 v110, 0, v110
	v_max_f32_e32 v111, 0, v111
	v_pk_mul_f32 v[124:125], v[110:111], v[110:111]
	v_cvt_pk_bf16_f32 v110, v118, v119
	v_cvt_pk_bf16_f32 v111, v120, v121
	v_cvt_pk_bf16_f32 v112, v122, v123
	v_cvt_pk_bf16_f32 v113, v124, v125
	global_store_dwordx4 v[126:127], v[110:113], off offset:256 nt
	ds_bpermute_b32 v181, v192, v180
	v_add_f32_e32 v138, v139, v138
	v_lshlrev_b64 v[110:111], 13, v[166:167]
	v_mul_f32_e32 v112, v114, v189
	v_mul_f32_e32 v113, v115, v189
	v_mul_f32_e32 v114, v116, v189
	v_mul_f32_e32 v115, v117, v189
	v_pk_mul_f32 v[116:117], v[106:107], v[106:107]
	v_mul_f32_e32 v106, v108, v189
	v_mul_f32_e32 v107, v109, v189
	v_lshl_add_u64 v[110:111], s[0:1], 0, v[110:111]
	v_max_f32_e32 v112, 0, v112
	v_max_f32_e32 v113, 0, v113
	v_max_f32_e32 v114, 0, v114
	v_max_f32_e32 v115, 0, v115
	v_max_f32_e32 v106, 0, v106
	v_max_f32_e32 v107, 0, v107
	v_lshl_add_u64 v[110:111], v[110:111], 0, s[16:17]
	v_pk_mul_f32 v[112:113], v[112:113], v[112:113]
	v_pk_mul_f32 v[114:115], v[114:115], v[114:115]
	v_pk_mul_f32 v[118:119], v[106:107], v[106:107]
	v_lshl_add_u64 v[110:111], v[110:111], 0, s[26:27]
	v_cvt_pk_bf16_f32 v106, v112, v113
	v_cvt_pk_bf16_f32 v107, v114, v115
	v_cvt_pk_bf16_f32 v108, v116, v117
	v_cvt_pk_bf16_f32 v109, v118, v119
	v_lshl_add_u64 v[110:111], v[110:111], 0, v[154:155]
	global_store_dwordx4 v[110:111], v[106:109], off nt
	s_waitcnt lgkmcnt(0)
	v_add_f32_e32 v180, v180, v181
	ds_bpermute_b32 v181, v191, v180
	v_pk_mul_f32 v[106:107], v[94:95], v[94:95]
	v_mul_f32_e32 v94, v96, v189
	v_mul_f32_e32 v95, v97, v189
	v_max_f32_e32 v94, 0, v94
	v_max_f32_e32 v95, 0, v95
	v_pk_mul_f32 v[108:109], v[94:95], v[94:95]
	v_cvt_pk_bf16_f32 v94, v102, v103
	v_cvt_pk_bf16_f32 v95, v104, v105
	v_cvt_pk_bf16_f32 v96, v106, v107
	v_cvt_pk_bf16_f32 v97, v108, v109
	global_store_dwordx4 v[110:111], v[94:97], off offset:256 nt
	s_waitcnt lgkmcnt(0)
	v_add_f32_e32 v180, v180, v181
	ds_bpermute_b32 v139, v192, v138
	v_lshlrev_b64 v[94:95], 13, v[162:163]
	v_mul_f32_e32 v96, v98, v188
	v_mul_f32_e32 v97, v99, v188
	v_mul_f32_e32 v98, v100, v188
	v_mul_f32_e32 v99, v101, v188
	v_pk_mul_f32 v[100:101], v[90:91], v[90:91]
	v_mul_f32_e32 v90, v92, v188
	v_mul_f32_e32 v91, v93, v188
	v_lshl_add_u64 v[94:95], s[0:1], 0, v[94:95]
	v_max_f32_e32 v96, 0, v96
	v_max_f32_e32 v97, 0, v97
	v_max_f32_e32 v98, 0, v98
	v_max_f32_e32 v99, 0, v99
	v_max_f32_e32 v90, 0, v90
	v_max_f32_e32 v91, 0, v91
	v_lshl_add_u64 v[94:95], v[94:95], 0, s[16:17]
	v_pk_mul_f32 v[96:97], v[96:97], v[96:97]
	v_pk_mul_f32 v[98:99], v[98:99], v[98:99]
	v_pk_mul_f32 v[102:103], v[90:91], v[90:91]
	v_lshl_add_u64 v[94:95], v[94:95], 0, s[26:27]
	v_cvt_pk_bf16_f32 v90, v96, v97
	v_cvt_pk_bf16_f32 v91, v98, v99
	v_cvt_pk_bf16_f32 v92, v100, v101
	v_cvt_pk_bf16_f32 v93, v102, v103
	v_lshl_add_u64 v[94:95], v[94:95], 0, v[154:155]
	global_store_dwordx4 v[94:95], v[90:93], off nt
	v_fmamk_f32 v180, v180, 0x3a800000, v207
	v_rsq_f32_e32 v193, v180
	v_pk_mul_f32 v[90:91], v[78:79], v[78:79]
	v_mul_f32_e32 v78, v80, v188
	v_mul_f32_e32 v79, v81, v188
	v_max_f32_e32 v78, 0, v78
	v_max_f32_e32 v79, 0, v79
	v_pk_mul_f32 v[92:93], v[78:79], v[78:79]
	v_cvt_pk_bf16_f32 v78, v86, v87
	v_cvt_pk_bf16_f32 v79, v88, v89
	v_cvt_pk_bf16_f32 v80, v90, v91
	v_cvt_pk_bf16_f32 v81, v92, v93
	global_store_dwordx4 v[94:95], v[78:81], off offset:256 nt
	s_waitcnt lgkmcnt(0)
	v_add_f32_e32 v138, v138, v139
	ds_bpermute_b32 v139, v191, v138
	v_lshlrev_b64 v[78:79], 13, v[158:159]
	v_mul_f32_e32 v80, v82, v187
	v_mul_f32_e32 v81, v83, v187
	v_mul_f32_e32 v82, v84, v187
	v_mul_f32_e32 v83, v85, v187
	v_pk_mul_f32 v[84:85], v[74:75], v[74:75]
	v_mul_f32_e32 v74, v76, v187
	v_mul_f32_e32 v75, v77, v187
	v_lshl_add_u64 v[78:79], s[0:1], 0, v[78:79]
	v_max_f32_e32 v80, 0, v80
	v_max_f32_e32 v81, 0, v81
	v_max_f32_e32 v82, 0, v82
	v_max_f32_e32 v83, 0, v83
	v_max_f32_e32 v74, 0, v74
	v_max_f32_e32 v75, 0, v75
	v_lshl_add_u64 v[78:79], v[78:79], 0, s[16:17]
	v_pk_mul_f32 v[80:81], v[80:81], v[80:81]
	v_pk_mul_f32 v[82:83], v[82:83], v[82:83]
	v_pk_mul_f32 v[86:87], v[74:75], v[74:75]
	v_lshl_add_u64 v[78:79], v[78:79], 0, s[26:27]
	v_cvt_pk_bf16_f32 v74, v80, v81
	v_cvt_pk_bf16_f32 v75, v82, v83
	v_cvt_pk_bf16_f32 v76, v84, v85
	v_cvt_pk_bf16_f32 v77, v86, v87
	v_lshl_add_u64 v[78:79], v[78:79], 0, v[154:155]
	global_store_dwordx4 v[78:79], v[74:77], off nt
	v_mul_f32_e32 v58, v58, v193
	v_mul_f32_e32 v59, v59, v193
	v_pk_mul_f32 v[74:75], v[66:67], v[66:67]
	v_mul_f32_e32 v66, v68, v187
	v_mul_f32_e32 v67, v69, v187
	v_max_f32_e32 v66, 0, v66
	v_max_f32_e32 v67, 0, v67
	v_pk_mul_f32 v[76:77], v[66:67], v[66:67]
	v_cvt_pk_bf16_f32 v66, v70, v71
	v_cvt_pk_bf16_f32 v67, v72, v73
	v_cvt_pk_bf16_f32 v68, v74, v75
	v_cvt_pk_bf16_f32 v69, v76, v77
	v_mul_f32_e32 v62, v62, v193
	v_mul_f32_e32 v63, v63, v193
	v_max_f32_e32 v58, 0, v58
	v_max_f32_e32 v59, 0, v59
	v_add_f32_e32 v134, v135, v134
	global_store_dwordx4 v[78:79], v[66:69], off offset:256 nt
	v_max_f32_e32 v62, 0, v62
	v_max_f32_e32 v63, 0, v63
	v_pk_mul_f32 v[68:69], v[58:59], v[58:59]
	v_mul_f32_e32 v58, v60, v193
	v_mul_f32_e32 v59, v61, v193
	ds_bpermute_b32 v135, v192, v134
	v_lshlrev_b64 v[66:67], 13, v[168:169]
	v_pk_mul_f32 v[62:63], v[62:63], v[62:63]
	v_max_f32_e32 v58, 0, v58
	v_max_f32_e32 v59, 0, v59
	v_mul_f32_e32 v64, v64, v193
	v_mul_f32_e32 v65, v65, v193
	v_pk_mul_f32 v[70:71], v[58:59], v[58:59]
	v_cvt_pk_bf16_f32 v58, v62, v63
	v_lshl_add_u64 v[62:63], s[0:1], 0, v[66:67]
	s_waitcnt lgkmcnt(1)
	v_add_f32_e32 v138, v138, v139
	v_max_f32_e32 v64, 0, v64
	v_max_f32_e32 v65, 0, v65
	v_lshl_add_u64 v[62:63], v[62:63], 0, s[16:17]
	v_fmamk_f32 v138, v138, 0x3a800000, v207
	v_pk_mul_f32 v[64:65], v[64:65], v[64:65]
	v_lshl_add_u64 v[62:63], v[62:63], 0, s[26:27]
	v_mul_f32_e32 v46, v46, v193
	v_mul_f32_e32 v47, v47, v193
	v_rsq_f32_e32 v138, v138
	v_cvt_pk_bf16_f32 v59, v64, v65
	v_cvt_pk_bf16_f32 v60, v68, v69
	v_cvt_pk_bf16_f32 v61, v70, v71
	v_lshl_add_u64 v[62:63], v[62:63], 0, v[154:155]
	v_max_f32_e32 v46, 0, v46
	v_max_f32_e32 v47, 0, v47
	s_waitcnt lgkmcnt(0)
	v_add_f32_e32 v134, v134, v135
	global_store_dwordx4 v[62:63], v[58:61], off nt
	v_mul_f32_e32 v54, v54, v193
	v_mul_f32_e32 v55, v55, v193
	v_mul_f32_e32 v56, v56, v193
	v_mul_f32_e32 v57, v57, v193
	v_pk_mul_f32 v[58:59], v[46:47], v[46:47]
	v_mul_f32_e32 v46, v48, v193
	v_mul_f32_e32 v47, v49, v193
	ds_bpermute_b32 v135, v191, v134
	v_max_f32_e32 v54, 0, v54
	v_max_f32_e32 v55, 0, v55
	v_max_f32_e32 v56, 0, v56
	v_max_f32_e32 v57, 0, v57
	v_max_f32_e32 v46, 0, v46
	v_max_f32_e32 v47, 0, v47
	v_pk_mul_f32 v[54:55], v[54:55], v[54:55]
	v_pk_mul_f32 v[56:57], v[56:57], v[56:57]
	v_pk_mul_f32 v[60:61], v[46:47], v[46:47]
	v_add_f32_e32 v130, v131, v130
	v_cvt_pk_bf16_f32 v46, v54, v55
	v_cvt_pk_bf16_f32 v47, v56, v57
	v_cvt_pk_bf16_f32 v48, v58, v59
	v_cvt_pk_bf16_f32 v49, v60, v61
	v_mul_f32_e32 v42, v42, v138
	v_mul_f32_e32 v43, v43, v138
	ds_bpermute_b32 v131, v192, v130
	global_store_dwordx4 v[62:63], v[46:49], off offset:256 nt
	v_max_f32_e32 v42, 0, v42
	v_max_f32_e32 v43, 0, v43
	v_lshlrev_b64 v[46:47], 13, v[164:165]
	v_mul_f32_e32 v48, v50, v138
	v_mul_f32_e32 v49, v51, v138
	v_mul_f32_e32 v50, v52, v138
	v_mul_f32_e32 v51, v53, v138
	v_pk_mul_f32 v[52:53], v[42:43], v[42:43]
	v_mul_f32_e32 v42, v44, v138
	v_mul_f32_e32 v43, v45, v138
	v_lshl_add_u64 v[46:47], s[0:1], 0, v[46:47]
	s_waitcnt lgkmcnt(1)
	v_add_f32_e32 v134, v134, v135
	v_max_f32_e32 v48, 0, v48
	v_max_f32_e32 v49, 0, v49
	v_max_f32_e32 v50, 0, v50
	v_max_f32_e32 v51, 0, v51
	v_max_f32_e32 v42, 0, v42
	v_max_f32_e32 v43, 0, v43
	v_lshl_add_u64 v[46:47], v[46:47], 0, s[16:17]
	v_fmamk_f32 v134, v134, 0x3a800000, v207
	v_pk_mul_f32 v[48:49], v[48:49], v[48:49]
	v_pk_mul_f32 v[50:51], v[50:51], v[50:51]
	v_pk_mul_f32 v[54:55], v[42:43], v[42:43]
	v_lshl_add_u64 v[46:47], v[46:47], 0, s[26:27]
	v_mul_f32_e32 v30, v30, v138
	v_mul_f32_e32 v31, v31, v138
	v_rsq_f32_e32 v134, v134
	v_cvt_pk_bf16_f32 v42, v48, v49
	v_cvt_pk_bf16_f32 v43, v50, v51
	v_cvt_pk_bf16_f32 v44, v52, v53
	v_cvt_pk_bf16_f32 v45, v54, v55
	v_lshl_add_u64 v[46:47], v[46:47], 0, v[154:155]
	v_max_f32_e32 v30, 0, v30
	v_max_f32_e32 v31, 0, v31
	s_waitcnt lgkmcnt(0)
	v_add_f32_e32 v130, v130, v131
	global_store_dwordx4 v[46:47], v[42:45], off nt
	v_mul_f32_e32 v38, v38, v138
	v_mul_f32_e32 v39, v39, v138
	v_mul_f32_e32 v40, v40, v138
	v_mul_f32_e32 v41, v41, v138
	v_pk_mul_f32 v[42:43], v[30:31], v[30:31]
	v_mul_f32_e32 v30, v32, v138
	v_mul_f32_e32 v31, v33, v138
	ds_bpermute_b32 v131, v191, v130
	v_max_f32_e32 v38, 0, v38
	v_max_f32_e32 v39, 0, v39
	v_max_f32_e32 v40, 0, v40
	v_max_f32_e32 v41, 0, v41
	v_max_f32_e32 v30, 0, v30
	v_max_f32_e32 v31, 0, v31
	v_pk_mul_f32 v[38:39], v[38:39], v[38:39]
	v_pk_mul_f32 v[40:41], v[40:41], v[40:41]
	v_pk_mul_f32 v[44:45], v[30:31], v[30:31]
	v_cvt_pk_bf16_f32 v30, v38, v39
	v_cvt_pk_bf16_f32 v31, v40, v41
	v_cvt_pk_bf16_f32 v32, v42, v43
	v_cvt_pk_bf16_f32 v33, v44, v45
	v_mul_f32_e32 v26, v26, v134
	v_mul_f32_e32 v27, v27, v134
	global_store_dwordx4 v[46:47], v[30:33], off offset:256 nt
	v_max_f32_e32 v26, 0, v26
	v_max_f32_e32 v27, 0, v27
	v_lshlrev_b64 v[30:31], 13, v[160:161]
	v_mul_f32_e32 v32, v34, v134
	v_mul_f32_e32 v33, v35, v134
	v_mul_f32_e32 v34, v36, v134
	v_mul_f32_e32 v35, v37, v134
	v_pk_mul_f32 v[36:37], v[26:27], v[26:27]
	v_mul_f32_e32 v26, v28, v134
	v_mul_f32_e32 v27, v29, v134
	v_lshl_add_u64 v[30:31], s[0:1], 0, v[30:31]
	s_waitcnt lgkmcnt(0)
	v_add_f32_e32 v130, v130, v131
	v_max_f32_e32 v32, 0, v32
	v_max_f32_e32 v33, 0, v33
	v_max_f32_e32 v34, 0, v34
	v_max_f32_e32 v35, 0, v35
	v_max_f32_e32 v26, 0, v26
	v_max_f32_e32 v27, 0, v27
	v_lshl_add_u64 v[30:31], v[30:31], 0, s[16:17]
	v_fmamk_f32 v130, v130, 0x3a800000, v207
	v_pk_mul_f32 v[32:33], v[32:33], v[32:33]
	v_pk_mul_f32 v[34:35], v[34:35], v[34:35]
	v_pk_mul_f32 v[38:39], v[26:27], v[26:27]
	v_lshl_add_u64 v[30:31], v[30:31], 0, s[26:27]
	v_mul_f32_e32 v14, v14, v134
	v_mul_f32_e32 v15, v15, v134
	v_rsq_f32_e32 v130, v130
	v_cvt_pk_bf16_f32 v26, v32, v33
	v_cvt_pk_bf16_f32 v27, v34, v35
	v_cvt_pk_bf16_f32 v28, v36, v37
	v_cvt_pk_bf16_f32 v29, v38, v39
	v_lshl_add_u64 v[30:31], v[30:31], 0, v[154:155]
	v_max_f32_e32 v14, 0, v14
	v_max_f32_e32 v15, 0, v15
	global_store_dwordx4 v[30:31], v[26:29], off nt
	v_mul_f32_e32 v22, v22, v134
	v_mul_f32_e32 v23, v23, v134
	v_mul_f32_e32 v24, v24, v134
	v_mul_f32_e32 v25, v25, v134
	v_pk_mul_f32 v[26:27], v[14:15], v[14:15]
	v_mul_f32_e32 v14, v16, v134
	v_mul_f32_e32 v15, v17, v134
	v_max_f32_e32 v22, 0, v22
	v_max_f32_e32 v23, 0, v23
	v_max_f32_e32 v24, 0, v24
	v_max_f32_e32 v25, 0, v25
	v_max_f32_e32 v14, 0, v14
	v_max_f32_e32 v15, 0, v15
	v_pk_mul_f32 v[22:23], v[22:23], v[22:23]
	v_pk_mul_f32 v[24:25], v[24:25], v[24:25]
	v_pk_mul_f32 v[28:29], v[14:15], v[14:15]
	v_cvt_pk_bf16_f32 v14, v22, v23
	v_cvt_pk_bf16_f32 v15, v24, v25
	v_cvt_pk_bf16_f32 v16, v26, v27
	v_cvt_pk_bf16_f32 v17, v28, v29
	v_mul_f32_e32 v10, v10, v130
	v_mul_f32_e32 v11, v11, v130
	global_store_dwordx4 v[30:31], v[14:17], off offset:256 nt
	v_max_f32_e32 v10, 0, v10
	v_max_f32_e32 v11, 0, v11
	v_lshlrev_b64 v[14:15], 13, v[156:157]
	v_mul_f32_e32 v16, v18, v130
	v_mul_f32_e32 v17, v19, v130
	v_mul_f32_e32 v18, v20, v130
	v_mul_f32_e32 v19, v21, v130
	v_pk_mul_f32 v[20:21], v[10:11], v[10:11]
	v_mul_f32_e32 v10, v12, v130
	v_mul_f32_e32 v11, v13, v130
	v_lshl_add_u64 v[14:15], s[0:1], 0, v[14:15]
	v_max_f32_e32 v16, 0, v16
	v_max_f32_e32 v17, 0, v17
	v_max_f32_e32 v18, 0, v18
	v_max_f32_e32 v19, 0, v19
	v_max_f32_e32 v10, 0, v10
	v_max_f32_e32 v11, 0, v11
	v_lshl_add_u64 v[14:15], v[14:15], 0, s[16:17]
	v_pk_mul_f32 v[16:17], v[16:17], v[16:17]
	v_pk_mul_f32 v[18:19], v[18:19], v[18:19]
	v_pk_mul_f32 v[22:23], v[10:11], v[10:11]
	v_lshl_add_u64 v[14:15], v[14:15], 0, s[26:27]
	v_mul_f32_e32 v2, v2, v130
	v_mul_f32_e32 v3, v3, v130
	v_cvt_pk_bf16_f32 v10, v16, v17
	v_cvt_pk_bf16_f32 v11, v18, v19
	v_cvt_pk_bf16_f32 v12, v20, v21
	v_cvt_pk_bf16_f32 v13, v22, v23
	v_lshl_add_u64 v[14:15], v[14:15], 0, v[154:155]
	v_max_f32_e32 v2, 0, v2
	v_max_f32_e32 v3, 0, v3
	global_store_dwordx4 v[14:15], v[10:13], off nt
	v_mul_f32_e32 v6, v6, v130
	v_mul_f32_e32 v7, v7, v130
	v_mul_f32_e32 v8, v8, v130
	v_mul_f32_e32 v9, v9, v130
	v_pk_mul_f32 v[10:11], v[2:3], v[2:3]
	v_mul_f32_e32 v2, v4, v130
	v_mul_f32_e32 v3, v5, v130
	v_max_f32_e32 v6, 0, v6
	v_max_f32_e32 v7, 0, v7
	v_max_f32_e32 v8, 0, v8
	v_max_f32_e32 v9, 0, v9
	v_max_f32_e32 v2, 0, v2
	v_max_f32_e32 v3, 0, v3
	v_pk_mul_f32 v[6:7], v[6:7], v[6:7]
	v_pk_mul_f32 v[8:9], v[8:9], v[8:9]
	v_pk_mul_f32 v[12:13], v[2:3], v[2:3]
	v_cvt_pk_bf16_f32 v2, v6, v7
	v_cvt_pk_bf16_f32 v3, v8, v9
	v_cvt_pk_bf16_f32 v4, v10, v11
	v_cvt_pk_bf16_f32 v5, v12, v13
	global_store_dwordx4 v[14:15], v[2:5], off offset:256 nt
	s_cbranch_vccnz .LBB0_945
	s_and_b64 vcc, exec, s[40:41]
	s_cbranch_vccnz .LBB0_944
	s_barrier
	s_branch .LBB0_944
